# nt on the f32 x row loads of P1/P4 (read once per phase)
# speedup vs baseline: 1.0550x; 1.0111x over previous
.LBB0_97:
	s_and_b64 s[0:1], s[0:1], exec
	s_cselect_b32 s1, s7, 0
	s_cselect_b32 s0, s6, s19
	s_cselect_b32 s19, s53, s55
	s_cselect_b32 s20, s52, s54
	s_lshl_b64 s[0:1], s[0:1], 12
	s_add_u32 s0, s20, s0
	s_addc_u32 s1, s19, s1
	global_load_dwordx4 v[50:53], v49, s[0:1] nt
	global_load_dwordx4 v[54:57], v49, s[0:1] offset:1024 nt
	global_load_dwordx4 v[58:61], v49, s[0:1] offset:3072 nt
	global_load_dwordx4 v[62:65], v49, s[0:1] offset:2048 nt
	s_add_u32 s6, s6, s8
	s_addc_u32 s7, s7, s9
	s_cmpk_lt_i32 s6, 0x2800
	s_waitcnt vmcnt(3)
	v_pk_mul_f32 v[66:67], v[52:53], v[52:53]
	v_pk_mul_f32 v[68:69], v[50:51], v[50:51]
	s_waitcnt vmcnt(2)
	v_pk_mul_f32 v[70:71], v[56:57], v[56:57]
	v_pk_mul_f32 v[72:73], v[54:55], v[54:55]
	v_pk_mov_b32 v[78:79], v[68:69], v[66:67] op_sel:[1,0]
	v_mov_b32_e32 v69, v67
	v_pk_mov_b32 v[66:67], v[72:73], v[70:71] op_sel:[1,0]
	v_mov_b32_e32 v73, v71
	s_waitcnt vmcnt(1)
	v_mul_f32_e32 v77, v60, v60
	s_waitcnt vmcnt(0)
	v_mul_f32_e32 v74, v63, v63
	v_mul_f32_e32 v76, v65, v65
	v_pk_add_f32 v[68:69], v[78:79], v[68:69]
	v_pk_add_f32 v[66:67], v[66:67], v[72:73]
	v_mul_f32_e32 v49, v58, v58
	v_mul_f32_e32 v80, v61, v61
	v_mul_f32_e32 v81, v59, v59
	v_pk_fma_f32 v[70:71], v[62:63], v[62:63], v[74:75] op_sel_hi:[1,1,0]
	v_pk_fma_f32 v[74:75], v[64:65], v[64:65], v[76:77] op_sel_hi:[1,1,0]
	v_pk_add_f32 v[68:69], v[68:69], v[68:69] op_sel:[0,1] op_sel_hi:[1,0]
	v_pk_add_f32 v[66:67], v[66:67], v[66:67] op_sel:[0,1] op_sel_hi:[1,0]
	v_mov_b32_e32 v71, v77
	v_mov_b32_e32 v75, v80
	v_mov_b32_e32 v69, v49
	v_mov_b32_e32 v67, v81
	v_pk_add_f32 v[70:71], v[70:71], v[74:75]
	v_pk_add_f32 v[66:67], v[68:69], v[66:67]
	s_nop 0
	v_pk_add_f32 v[66:67], v[66:67], v[70:71]
	s_nop 0
	v_add_f32_e32 v49, v66, v67
	ds_bpermute_b32 v66, v1, v49
	s_waitcnt lgkmcnt(0)
	v_add_f32_e32 v49, v49, v66
	ds_bpermute_b32 v66, v35, v49
	s_waitcnt lgkmcnt(0)
	v_add_f32_e32 v49, v49, v66
	ds_bpermute_b32 v66, v40, v49
	s_waitcnt lgkmcnt(0)
	v_add_f32_e32 v49, v49, v66
	ds_bpermute_b32 v66, v41, v49
	s_waitcnt lgkmcnt(0)
	v_add_f32_e32 v49, v49, v66
	ds_bpermute_b32 v66, v42, v49
	s_waitcnt lgkmcnt(0)
	v_add_f32_e32 v49, v49, v66
	ds_bpermute_b32 v66, v43, v49
	s_waitcnt lgkmcnt(0)
	v_add_f32_e32 v49, v49, v66
	v_fmamk_f32 v49, v49, 0x3a800000, v47
	v_mul_f32_e32 v66, 0x4f800000, v49
	v_cmp_gt_f32_e32 vcc, s18, v49
	s_nop 1
	v_cndmask_b32_e32 v49, v49, v66, vcc
	v_sqrt_f32_e32 v66, v49
	s_nop 0
	v_add_u32_e32 v67, -1, v66
	v_add_u32_e32 v68, 1, v66
	v_fma_f32 v69, -v67, v66, v49
	v_fma_f32 v70, -v68, v66, v49
	v_cmp_ge_f32_e64 s[0:1], 0, v69
	s_nop 1
	v_cndmask_b32_e64 v66, v66, v67, s[0:1]
	v_cmp_lt_f32_e64 s[0:1], 0, v70
	s_nop 1
	v_cndmask_b32_e64 v66, v66, v68, s[0:1]
	v_mul_f32_e32 v67, 0x37800000, v66
	v_cndmask_b32_e32 v66, v66, v67, vcc
	v_cmp_class_f32_e32 vcc, v49, v48
	s_nop 1
	v_cndmask_b32_e32 v49, v66, v49, vcc
	v_div_scale_f32 v66, s[0:1], v49, v49, 1.0
	v_rcp_f32_e32 v67, v66
	v_div_scale_f32 v68, vcc, 1.0, v49, 1.0
	v_fma_f32 v69, -v66, v67, 1.0
	v_fmac_f32_e32 v67, v69, v67
	v_mul_f32_e32 v69, v68, v67
	v_fma_f32 v70, -v66, v69, v68
	v_fmac_f32_e32 v69, v70, v67
	v_fma_f32 v66, -v66, v69, v68
	v_div_fmas_f32 v66, v66, v67, v69
	v_div_fixup_f32 v66, v66, v49, 1.0
	v_pk_mul_f32 v[50:51], v[50:51], v[66:67] op_sel_hi:[1,0]
	v_pk_mul_f32 v[52:53], v[52:53], v[66:67] op_sel_hi:[1,0]
	v_pk_mul_f32 v[54:55], v[54:55], v[66:67] op_sel_hi:[1,0]
	v_pk_mul_f32 v[56:57], v[56:57], v[66:67] op_sel_hi:[1,0]
	v_pk_mul_f32 v[62:63], v[62:63], v[66:67] op_sel_hi:[1,0]
	v_pk_mul_f32 v[64:65], v[64:65], v[66:67] op_sel_hi:[1,0]
	v_pk_mul_f32 v[58:59], v[58:59], v[66:67] op_sel_hi:[1,0]
	v_pk_mul_f32 v[60:61], v[60:61], v[66:67] op_sel_hi:[1,0]
	v_pk_fma_f32 v[52:53], v[20:21], v[52:53], v[4:5]
	v_pk_fma_f32 v[50:51], v[18:19], v[50:51], v[2:3]
	v_pk_fma_f32 v[56:57], v[24:25], v[56:57], v[12:13]
	v_pk_fma_f32 v[54:55], v[22:23], v[54:55], v[10:11]
	v_pk_fma_f32 v[64:65], v[28:29], v[64:65], v[8:9]
	v_pk_fma_f32 v[62:63], v[26:27], v[62:63], v[6:7]
	v_pk_fma_f32 v[60:61], v[32:33], v[60:61], v[16:17]
	v_pk_fma_f32 v[58:59], v[30:31], v[58:59], v[14:15]
	v_cvt_pk_bf16_f32 v50, v50, v51
	v_cvt_pk_bf16_f32 v51, v52, v53
	v_cvt_pk_bf16_f32 v52, v54, v55
	v_cvt_pk_bf16_f32 v53, v56, v57
	v_cvt_pk_bf16_f32 v54, v62, v63
	v_cvt_pk_bf16_f32 v55, v64, v65
	v_cvt_pk_bf16_f32 v56, v58, v59
	v_cvt_pk_bf16_f32 v57, v60, v61
	global_store_dwordx2 v[38:39], v[50:51], off sc1
	global_store_dwordx2 v[38:39], v[52:53], off offset:512 sc1
	global_store_dwordx2 v[38:39], v[54:55], off offset:1024 sc1
	global_store_dwordx2 v[38:39], v[56:57], off offset:1536 sc1
	v_lshl_add_u64 v[38:39], v[38:39], 0, s[12:13]
	s_cbranch_scc0 .LBB0_100

.LBB0_385:
	v_add_co_u32_e32 v74, vcc, s20, v62
	s_and_b64 s[0:1], s[0:1], exec
	s_nop 0
	v_addc_co_u32_e32 v75, vcc, -1, v63, vcc
	global_load_dwordx2 v[78:79], v[74:75], off offset:-1536 nt
	global_load_dwordx2 v[80:81], v[74:75], off offset:-1024 nt
	global_load_dwordx2 v[82:83], v[74:75], off offset:-512 nt
	global_load_dwordx2 v[84:85], v[74:75], off nt
	s_cselect_b32 s1, s7, 0
	s_cselect_b32 s0, s6, s23
	s_cselect_b32 s14, s53, s55
	s_cselect_b32 s15, s52, s54
	s_lshl_b64 s[0:1], s[0:1], 12
	s_add_u32 s0, s15, s0
	s_addc_u32 s1, s14, s1
	global_load_dwordx4 v[74:77], v73, s[0:1] nt
	s_add_u32 s6, s6, s8
	s_addc_u32 s7, s7, s9
	s_cmp_lt_i32 s6, s98
	s_waitcnt vmcnt(0)
	v_and_b32_e32 v91, 0xffff0000, v78
	v_and_b32_e32 v93, 0xffff0000, v79
	v_lshlrev_b32_e32 v90, 16, v78
	v_lshlrev_b32_e32 v103, 16, v84
	v_lshlrev_b32_e32 v92, 16, v79
	v_and_b32_e32 v97, 0xffff0000, v81
	v_and_b32_e32 v96, 0xffff0000, v80
	v_lshlrev_b32_e32 v98, 16, v82
	v_and_b32_e32 v99, 0xffff0000, v82
	v_mul_f32_e32 v78, v93, v93
	v_mul_f32_e32 v82, v91, v91
	v_mov_b32_e32 v79, v103
	v_lshlrev_b32_e32 v95, 16, v81
	v_lshlrev_b32_e32 v94, 16, v80
	v_lshlrev_b32_e32 v100, 16, v83
	v_and_b32_e32 v101, 0xffff0000, v83
	v_pk_mul_f32 v[80:81], v[96:97], v[96:97]
	v_pk_fma_f32 v[88:89], v[92:93], v[92:93], v[78:79] op_sel_hi:[1,1,0]
	v_pk_fma_f32 v[82:83], v[90:91], v[90:91], v[82:83] op_sel_hi:[1,1,0]
	v_and_b32_e32 v105, 0xffff0000, v84
	v_lshlrev_b32_e32 v106, 16, v85
	v_and_b32_e32 v107, 0xffff0000, v85
	v_mul_f32_e32 v84, v99, v99
	v_mul_f32_e32 v86, v101, v101
	v_pk_fma_f32 v[80:81], v[94:95], v[94:95], v[80:81]
	v_mov_b32_e32 v102, v82
	v_mov_b32_e32 v78, v88
	v_mul_f32_e32 v104, v105, v105
	v_mul_f32_e32 v108, v106, v106
	v_mul_f32_e32 v109, v107, v107
	v_pk_fma_f32 v[84:85], v[98:99], v[98:99], v[84:85] op_sel_hi:[1,1,0]
	v_pk_fma_f32 v[86:87], v[100:101], v[100:101], v[86:87] op_sel_hi:[1,1,0]
	v_pk_add_f32 v[82:83], v[82:83], v[88:89]
	v_pk_add_f32 v[80:81], v[80:81], v[80:81] op_sel:[0,1] op_sel_hi:[1,0]
	v_pk_mul_f32 v[78:79], v[102:103], v[78:79]
	v_mov_b32_e32 v85, v108
	v_mov_b32_e32 v87, v109
	v_mov_b32_e32 v81, v104
	v_mov_b32_e32 v83, v79
	v_pk_add_f32 v[84:85], v[84:85], v[86:87]
	v_pk_add_f32 v[78:79], v[82:83], v[80:81]
	v_mov_b32_e32 v108, v94
	v_pk_add_f32 v[78:79], v[78:79], v[84:85]
	v_mov_b32_e32 v109, v96
	v_add_f32_e32 v102, v78, v79
	global_load_dwordx4 v[78:81], v73, s[0:1] offset:1024 nt
	global_load_dwordx4 v[82:85], v73, s[0:1] offset:2048 nt
	global_load_dwordx4 v[86:89], v73, s[0:1] offset:3072 nt
	ds_bpermute_b32 v104, v1, v102
	v_mov_b32_e32 v96, v95
	s_waitcnt lgkmcnt(0)
	v_add_f32_e32 v73, v102, v104
	ds_bpermute_b32 v102, v51, v73
	s_waitcnt lgkmcnt(0)
	v_add_f32_e32 v73, v73, v102
	ds_bpermute_b32 v102, v64, v73
	s_waitcnt lgkmcnt(0)
	v_add_f32_e32 v73, v73, v102
	ds_bpermute_b32 v102, v65, v73
	s_waitcnt lgkmcnt(0)
	v_add_f32_e32 v73, v73, v102
	ds_bpermute_b32 v102, v66, v73
	s_waitcnt lgkmcnt(0)
	v_add_f32_e32 v73, v73, v102
	ds_bpermute_b32 v102, v67, v73
	s_waitcnt lgkmcnt(0)
	v_add_f32_e32 v73, v73, v102
	v_fmamk_f32 v73, v73, 0x3a800000, v71
	v_mul_f32_e32 v102, 0x4f800000, v73
	v_cmp_gt_f32_e32 vcc, s21, v73
	s_nop 1
	v_cndmask_b32_e32 v73, v73, v102, vcc
	v_sqrt_f32_e32 v102, v73
	s_nop 0
	v_add_u32_e32 v94, -1, v102
	v_add_u32_e32 v95, 1, v102
	v_fma_f32 v104, -v94, v102, v73
	v_fma_f32 v110, -v95, v102, v73
	v_cmp_ge_f32_e64 s[0:1], 0, v104
	v_mov_b32_e32 v104, v103
	s_nop 0
	v_cndmask_b32_e64 v94, v102, v94, s[0:1]
	v_cmp_lt_f32_e64 s[0:1], 0, v110
	s_nop 1
	v_cndmask_b32_e64 v94, v94, v95, s[0:1]
	v_mul_f32_e32 v95, 0x37800000, v94
	v_cndmask_b32_e32 v94, v94, v95, vcc
	v_cmp_class_f32_e32 vcc, v73, v72
	s_nop 1
	v_cndmask_b32_e32 v73, v94, v73, vcc
	v_div_scale_f32 v94, s[0:1], v73, v73, 1.0
	v_rcp_f32_e32 v95, v94
	v_div_scale_f32 v102, vcc, 1.0, v73, 1.0
	v_fma_f32 v103, -v94, v95, 1.0
	v_fmac_f32_e32 v95, v103, v95
	v_mul_f32_e32 v103, v102, v95
	v_fma_f32 v110, -v94, v103, v102
	v_fmac_f32_e32 v103, v110, v95
	v_fma_f32 v94, -v94, v103, v102
	v_div_fmas_f32 v94, v94, v95, v103
	v_div_fixup_f32 v94, v94, v73, 1.0
	v_pk_mul_f32 v[90:91], v[94:95], v[90:91] op_sel_hi:[0,1]
	v_pk_mul_f32 v[92:93], v[94:95], v[92:93] op_sel_hi:[0,1]
	v_pk_mul_f32 v[102:103], v[94:95], v[108:109] op_sel_hi:[0,1]
	v_pk_mul_f32 v[96:97], v[94:95], v[96:97] op_sel_hi:[0,1]
	v_pk_mul_f32 v[98:99], v[94:95], v[98:99] op_sel_hi:[0,1]
	v_pk_mul_f32 v[100:101], v[94:95], v[100:101] op_sel_hi:[0,1]
	v_pk_mul_f32 v[104:105], v[104:105], v[94:95] op_sel_hi:[1,0]
	v_pk_mul_f32 v[94:95], v[106:107], v[94:95] op_sel_hi:[1,0]
	v_pk_fma_f32 v[76:77], v[16:17], v[92:93], v[76:77]
	v_pk_fma_f32 v[74:75], v[14:15], v[90:91], v[74:75]
	s_waitcnt vmcnt(2)
	v_pk_fma_f32 v[80:81], v[28:29], v[96:97], v[80:81]
	v_pk_fma_f32 v[78:79], v[26:27], v[102:103], v[78:79]
	s_waitcnt vmcnt(0)
	v_pk_fma_f32 v[88:89], v[24:25], v[94:95], v[88:89]
	v_pk_mul_f32 v[90:91], v[76:77], v[76:77]
	v_pk_mul_f32 v[92:93], v[74:75], v[74:75]
	v_pk_mul_f32 v[94:95], v[80:81], v[80:81]
	v_pk_mul_f32 v[96:97], v[78:79], v[78:79]
	v_pk_fma_f32 v[84:85], v[32:33], v[100:101], v[84:85]
	v_pk_fma_f32 v[82:83], v[30:31], v[98:99], v[82:83]
	v_pk_mov_b32 v[102:103], v[92:93], v[90:91] op_sel:[1,0]
	v_mov_b32_e32 v93, v91
	v_pk_mov_b32 v[90:91], v[96:97], v[94:95] op_sel:[1,0]
	v_mov_b32_e32 v97, v95
	v_mul_f32_e32 v98, v82, v82
	v_mul_f32_e32 v100, v84, v84
	v_pk_add_f32 v[92:93], v[102:103], v[92:93]
	v_pk_add_f32 v[90:91], v[90:91], v[96:97]
	v_pk_fma_f32 v[86:87], v[22:23], v[104:105], v[86:87]
	v_pk_fma_f32 v[94:95], v[82:83], v[82:83], v[98:99] op_sel_hi:[1,1,0]
	v_pk_fma_f32 v[98:99], v[84:85], v[84:85], v[100:101] op_sel_hi:[1,1,0]
	v_pk_add_f32 v[92:93], v[92:93], v[92:93] op_sel_hi:[0,1]
	v_pk_add_f32 v[90:91], v[90:91], v[90:91] op_sel_hi:[0,1]
	v_mul_f32_e32 v94, v86, v86
	v_mul_f32_e32 v98, v87, v87
	v_mul_f32_e32 v92, v88, v88
	v_mul_f32_e32 v90, v89, v89
	v_pk_add_f32 v[94:95], v[94:95], v[98:99]
	v_pk_add_f32 v[90:91], v[92:93], v[90:91]
	v_cvt_pk_bf16_f32 v93, v76, v77
	v_pk_add_f32 v[90:91], v[94:95], v[90:91]
	v_cvt_pk_bf16_f32 v94, v78, v79
	v_add_f32_e32 v73, v90, v91
	ds_bpermute_b32 v90, v1, v73
	v_cvt_pk_bf16_f32 v95, v80, v81
	v_cvt_pk_bf16_f32 v97, v84, v85
	v_cvt_pk_bf16_f32 v98, v86, v87
	v_cvt_pk_bf16_f32 v99, v88, v89
	s_waitcnt lgkmcnt(0)
	v_add_f32_e32 v73, v73, v90
	ds_bpermute_b32 v90, v51, v73
	s_waitcnt lgkmcnt(0)
	v_add_f32_e32 v73, v73, v90
	ds_bpermute_b32 v90, v64, v73
	s_waitcnt lgkmcnt(0)
	v_add_f32_e32 v73, v73, v90
	ds_bpermute_b32 v92, v65, v73
	v_add_co_u32_e32 v90, vcc, s22, v62
	s_waitcnt lgkmcnt(0)
	v_add_f32_e32 v73, v73, v92
	ds_bpermute_b32 v96, v66, v73
	v_addc_co_u32_e32 v91, vcc, -1, v63, vcc
	v_cvt_pk_bf16_f32 v92, v74, v75
	s_waitcnt lgkmcnt(0)
	v_add_f32_e32 v73, v73, v96
	ds_bpermute_b32 v100, v67, v73
	v_cvt_pk_bf16_f32 v96, v82, v83
	global_store_dwordx2 v[62:63], v[92:93], off offset:-1536 sc1
	global_store_dwordx2 v[62:63], v[94:95], off offset:-1024 sc1
	global_store_dwordx2 v[62:63], v[96:97], off offset:-512 sc1
	global_store_dwordx2 v[62:63], v[98:99], off sc1
	v_lshl_add_u64 v[62:63], v[62:63], 0, s[12:13]
	s_waitcnt lgkmcnt(0)
	v_add_f32_e32 v73, v73, v100
	v_fmamk_f32 v73, v73, 0x3a800000, v71
	v_mul_f32_e32 v100, 0x4f800000, v73
	v_cmp_gt_f32_e32 vcc, s21, v73
	s_nop 1
	v_cndmask_b32_e32 v73, v73, v100, vcc
	v_sqrt_f32_e32 v100, v73
	s_nop 0
	v_add_u32_e32 v92, -1, v100
	v_add_u32_e32 v93, 1, v100
	v_fma_f32 v94, -v92, v100, v73
	v_fma_f32 v95, -v93, v100, v73
	v_cmp_ge_f32_e64 s[0:1], 0, v94
	s_nop 1
	v_cndmask_b32_e64 v92, v100, v92, s[0:1]
	v_cmp_lt_f32_e64 s[0:1], 0, v95
	s_nop 1
	v_cndmask_b32_e64 v92, v92, v93, s[0:1]
	v_mul_f32_e32 v93, 0x37800000, v92
	v_cndmask_b32_e32 v92, v92, v93, vcc
	v_cmp_class_f32_e32 vcc, v73, v72
	s_nop 1
	v_cndmask_b32_e32 v73, v92, v73, vcc
	v_div_scale_f32 v92, s[0:1], v73, v73, 1.0
	v_rcp_f32_e32 v93, v92
	v_div_scale_f32 v94, vcc, 1.0, v73, 1.0
	v_fma_f32 v95, -v92, v93, 1.0
	v_fmac_f32_e32 v93, v95, v93
	v_mul_f32_e32 v95, v94, v93
	v_fma_f32 v96, -v92, v95, v94
	v_fmac_f32_e32 v95, v96, v93
	v_fma_f32 v92, -v92, v95, v94
	v_div_fmas_f32 v92, v92, v93, v95
	v_div_fixup_f32 v92, v92, v73, 1.0
	v_pk_mul_f32 v[74:75], v[74:75], v[92:93] op_sel_hi:[1,0]
	v_pk_mul_f32 v[76:77], v[76:77], v[92:93] op_sel_hi:[1,0]
	v_pk_mul_f32 v[78:79], v[78:79], v[92:93] op_sel_hi:[1,0]
	v_pk_mul_f32 v[80:81], v[80:81], v[92:93] op_sel_hi:[1,0]
	v_pk_mul_f32 v[82:83], v[82:83], v[92:93] op_sel_hi:[1,0]
	v_pk_mul_f32 v[84:85], v[84:85], v[92:93] op_sel_hi:[1,0]
	v_pk_fma_f32 v[76:77], v[36:37], v[76:77], v[20:21]
	v_pk_fma_f32 v[74:75], v[34:35], v[74:75], v[18:19]
	v_pk_fma_f32 v[80:81], v[40:41], v[80:81], v[4:5]
	v_pk_fma_f32 v[78:79], v[38:39], v[78:79], v[2:3]
	v_pk_fma_f32 v[84:85], v[44:45], v[84:85], v[12:13]
	v_pk_fma_f32 v[82:83], v[42:43], v[82:83], v[10:11]
	v_cvt_pk_bf16_f32 v74, v74, v75
	v_cvt_pk_bf16_f32 v75, v76, v77
	v_cvt_pk_bf16_f32 v76, v78, v79
	v_cvt_pk_bf16_f32 v77, v80, v81
	v_cvt_pk_bf16_f32 v78, v82, v83
	v_cvt_pk_bf16_f32 v79, v84, v85
	global_store_dwordx2 v[90:91], v[74:75], off offset:-1536 sc1
	global_store_dwordx2 v[90:91], v[76:77], off offset:-1024 sc1
	global_store_dwordx2 v[90:91], v[78:79], off offset:-512 sc1
	v_pk_mul_f32 v[74:75], v[86:87], v[92:93] op_sel_hi:[1,0]
	v_pk_mul_f32 v[76:77], v[88:89], v[92:93] op_sel_hi:[1,0]
	v_pk_fma_f32 v[74:75], v[46:47], v[74:75], v[6:7]
	v_pk_fma_f32 v[76:77], v[48:49], v[76:77], v[8:9]
	v_cvt_pk_bf16_f32 v74, v74, v75
	v_cvt_pk_bf16_f32 v75, v76, v77
	global_store_dwordx2 v[90:91], v[74:75], off sc1
	s_cbranch_scc0 .LBB0_388
